# fast XCD-local barrier also on ffn1 up->down (layer>0) and ffn2down->next layer ffn1up (not last layer)
# speedup vs baseline: 1.0407x; 1.0048x over previous
.LBB0_145:
	s_waitcnt vmcnt(0)
	v_mov_b32_e32 v1, v218
	s_waitcnt vmcnt(0) lgkmcnt(0)
	s_barrier
	s_nop 0
	v_cmp_eq_u32_e32 vcc, 0, v1
	s_and_saveexec_b64 s[2:3], vcc
	s_cbranch_execz .LBB0_197
	v_readlane_b32 s101, v255, 12
	s_nop 3
	s_cmp_eq_u32 s101, 0
	s_cbranch_scc1 .Lfb_slow_1
	v_readlane_b32 s100, v255, 40
	s_nop 3
	s_cmp_eq_u32 s100, 0
	s_cbranch_scc1 .Lfb_slow_1
	v_readlane_b32 s100, v255, 41
	v_readlane_b32 s101, v255, 42
	v_mov_b32_e32 v2, 0
	v_mov_b32_e32 v3, 1
	v_mov_b32_e32 v4, 1
	s_nop 2
	global_atomic_add v3, v2, v3, s[100:101] sc0
	s_waitcnt vmcnt(0)
	v_readfirstlane_b32 vcc_hi, v3
	s_nop 3
	s_lshr_b32 vcc_lo, vcc_hi, 5
	s_add_i32 vcc_hi, vcc_hi, 1
	s_and_b32 vcc_hi, vcc_hi, 31
	s_cmp_lg_u32 vcc_hi, 0
	s_cbranch_scc1 .Lfb_spin_1
	global_atomic_add v2, v4, s[100:101] offset:128
	s_branch .Lfb_done_1

.Lfb_slow_1:
	v_mov_b32_e32 v1, s84
	s_getreg_b32 s6, hwreg(HW_REG_XCC_ID, 0, 4)
	s_waitcnt vmcnt(0) expcnt(0) lgkmcnt(0)
	ds_read_b32 v3, v1
	v_mov_b32_e32 v1, s85
	ds_read_b32 v2, v1
	s_and_b32 s50, s6, 15
	s_waitcnt lgkmcnt(1)
	v_cmp_ne_u32_e32 vcc, 0, v3
	s_cbranch_vccnz .LBB0_161
	s_add_u32 s6, s4, 0x10200
	s_addc_u32 s7, s5, 0
	s_add_u32 s8, s4, 0x10400
	s_addc_u32 s9, s5, 0
	s_add_u32 s10, s4, 0x10500
	s_addc_u32 s11, s5, 0
	s_add_u32 s14, s4, 0x10600
	s_addc_u32 s15, s5, 0
	s_add_u32 s16, s4, 0x10700
	s_addc_u32 s17, s5, 0
	s_add_u32 s18, s4, 0x10800
	s_addc_u32 s19, s5, 0
	s_add_u32 s20, s4, 0x10900
	s_addc_u32 s21, s5, 0
	s_add_u32 s22, s4, 0x10a00
	s_addc_u32 s23, s5, 0
	s_add_u32 s24, s4, 0x10b00
	s_addc_u32 s25, s5, 0
	s_add_u32 s26, s4, 0x10c00
	s_addc_u32 s27, s5, 0
	s_add_u32 s28, s4, 0x10d00
	s_addc_u32 s29, s5, 0
	s_add_u32 s30, s4, 0x10e00
	s_addc_u32 s31, s5, 0
	s_add_u32 s34, s4, 0x10f00
	s_addc_u32 s35, s5, 0
	s_add_u32 s36, s4, 0x11000
	s_addc_u32 s37, s5, 0
	s_add_u32 s38, s4, 0x11100
	s_addc_u32 s39, s5, 0
	s_add_u32 s40, s4, 0x11200
	s_addc_u32 s41, s5, 0
	s_add_u32 s42, s4, 0x11300
	s_addc_u32 s43, s5, 0
	s_mov_b32 s51, 1
	s_branch .LBB0_149

.Lfb_lb10:
	s_getpc_b64 s[98:99]

.LBB0_1287:
	v_readlane_b32 s101, v255, 12
	s_nop 3
	s_cmp_lg_u32 s101, 0
	s_cbranch_scc1 .Lfb_slow_10
	v_readlane_b32 s100, v255, 40
	s_nop 3
	s_cmp_eq_u32 s100, 0
	s_cbranch_scc1 .Lfb_slow_10
	v_readlane_b32 s100, v255, 41
	v_readlane_b32 s101, v255, 42
	v_mov_b32_e32 v2, 0
	v_mov_b32_e32 v3, 1
	v_mov_b32_e32 v4, 1
	s_nop 2
	global_atomic_add v3, v2, v3, s[100:101] sc0
	s_waitcnt vmcnt(0)
	v_readfirstlane_b32 vcc_hi, v3
	s_nop 3
	s_lshr_b32 vcc_lo, vcc_hi, 5
	s_add_i32 vcc_hi, vcc_hi, 1
	s_and_b32 vcc_hi, vcc_hi, 31
	s_cmp_lg_u32 vcc_hi, 0
	s_cbranch_scc1 .Lfb_spin_10
	global_atomic_add v2, v4, s[100:101] offset:128
	s_branch .Lfb_done_10

.Lfb_done_10:
	buffer_inv sc1
	s_waitcnt vmcnt(0)
	s_branch .Lfb_lb10
.Lfb_slow_10:
	v_mov_b32_e32 v1, s84
	s_getreg_b32 s4, hwreg(HW_REG_XCC_ID, 0, 4)
	s_waitcnt vmcnt(0) expcnt(0) lgkmcnt(0)
	ds_read_b32 v3, v1
	v_mov_b32_e32 v1, s85
	ds_read_b32 v1, v1
	s_and_b32 s48, s4, 15
	s_waitcnt lgkmcnt(1)
	v_cmp_ne_u32_e32 vcc, 0, v3
	s_cbranch_vccnz .LBB0_1302
	s_add_u32 s4, s6, 0x10200
	s_addc_u32 s5, s7, 0
	s_add_u32 s8, s6, 0x10400
	s_addc_u32 s9, s7, 0
	s_add_u32 s10, s6, 0x10500
	s_addc_u32 s11, s7, 0
	s_add_u32 s12, s6, 0x10600
	s_addc_u32 s13, s7, 0
	s_add_u32 s14, s6, 0x10700
	s_addc_u32 s15, s7, 0
	s_add_u32 s16, s6, 0x10800
	s_addc_u32 s17, s7, 0
	s_add_u32 s18, s6, 0x10900
	s_addc_u32 s19, s7, 0
	s_add_u32 s20, s6, 0x10a00
	s_addc_u32 s21, s7, 0
	s_add_u32 s22, s6, 0x10b00
	s_addc_u32 s23, s7, 0
	s_add_u32 s24, s6, 0x10c00
	s_addc_u32 s25, s7, 0
	s_add_u32 s26, s6, 0x10d00
	s_addc_u32 s27, s7, 0
	s_add_u32 s28, s6, 0x10e00
	s_addc_u32 s29, s7, 0
	s_add_u32 s30, s6, 0x10f00
	s_addc_u32 s31, s7, 0
	s_add_u32 s34, s6, 0x11000
	s_addc_u32 s35, s7, 0
	s_add_u32 s36, s6, 0x11100
	s_addc_u32 s37, s7, 0
	s_add_u32 s38, s6, 0x11200
	s_addc_u32 s39, s7, 0
	s_add_u32 s40, s6, 0x11300
	s_addc_u32 s41, s7, 0
	s_mov_b32 s49, 1
	s_branch .LBB0_1290
